# mLSTM state phase: next item's prefetch loads issued after the conv staging loop (its conv-weight waits no longer wait for the prefetch)
# baseline (speedup 1.0000x reference)
; DEVI void lds_barrier() { asm volatile("s_waitcnt lgkmcnt(0)\n\ts_barrier" ::: "memory"); }
; template <int KIND>
; DEVI void mix_state_phase(unsigned char* smem, const MixArgs a) {
;     ...
;         lds_barrier();
;         if (item + (int)gridDim.x < 16 * NCH) ST_PREF(item + (int)gridDim.x);
;         (void)c;
;         if (KIND == 0) {
;             if (tid < 64) { float x0 = fB[2 * tid], x1 = fB[2 * tid + 1]; float sc = x0 + x1;
; #pragma unroll
;                 for (int o = 1; o < 64; o <<= 1) { const float t = __shfl_up(sc, o); if (tid >= o) sc += t; }
;                 fB[2 * tid] = sc - x1; fB[2 * tid + 1] = sc; }
.LBB0_546:
	s_or_b64 exec, exec, s[88:89]
	s_add_i32 s46, s86, s22
	s_waitcnt lgkmcnt(0)
	s_barrier
.LBB0_560:
	s_and_saveexec_b64 s[88:89], s[4:5]
	s_cbranch_execz .LBB0_562
	v_add_u32_e32 v8, 0, v107
	ds_read_b64 v[10:11], v8
	v_and_b32_e32 v56, 64, v155
	v_add_u32_e32 v57, -1, v155
	v_cmp_lt_i32_e32 vcc, v57, v56
	v_readlane_b32 s18, v254, 29
	s_waitcnt lgkmcnt(0)
	v_add_f32_e32 v10, v10, v11
	v_cndmask_b32_e32 v57, v57, v155, vcc
	v_lshlrev_b32_e32 v57, 2, v57
	ds_bpermute_b32 v57, v57, v10
	v_readlane_b32 s19, v254, 30
	s_waitcnt lgkmcnt(0)
	v_add_f32_e32 v57, v10, v57
	v_cndmask_b32_e64 v10, v57, v10, s[18:19]
	v_add_u32_e32 v57, -2, v155
	v_cmp_lt_i32_e32 vcc, v57, v56
	v_readlane_b32 s18, v254, 31
	v_readlane_b32 s19, v254, 32
	v_cndmask_b32_e32 v57, v57, v155, vcc
	v_lshlrev_b32_e32 v57, 2, v57
	ds_bpermute_b32 v57, v57, v10
	s_waitcnt lgkmcnt(0)
	v_add_f32_e32 v57, v10, v57
	v_cndmask_b32_e64 v10, v57, v10, s[18:19]
	v_add_u32_e32 v57, -4, v155
	v_cmp_lt_i32_e32 vcc, v57, v56
	v_readlane_b32 s18, v254, 33
	v_readlane_b32 s19, v254, 34
	v_cndmask_b32_e32 v57, v57, v155, vcc
	v_lshlrev_b32_e32 v57, 2, v57
	ds_bpermute_b32 v57, v57, v10
	s_waitcnt lgkmcnt(0)
	v_add_f32_e32 v57, v10, v57
	v_cndmask_b32_e64 v10, v57, v10, s[18:19]
	v_add_u32_e32 v57, -8, v155
	v_cmp_lt_i32_e32 vcc, v57, v56
	v_readlane_b32 s18, v254, 35
	v_readlane_b32 s19, v254, 36
	v_cndmask_b32_e32 v57, v57, v155, vcc
	v_lshlrev_b32_e32 v57, 2, v57
	ds_bpermute_b32 v57, v57, v10
	s_waitcnt lgkmcnt(0)
	v_add_f32_e32 v57, v10, v57
	v_cndmask_b32_e64 v10, v57, v10, s[18:19]
	v_add_u32_e32 v57, -16, v155
	v_cmp_lt_i32_e32 vcc, v57, v56
	v_readlane_b32 s18, v254, 37
	v_readlane_b32 s19, v254, 38
	v_cndmask_b32_e32 v57, v57, v155, vcc
	v_lshlrev_b32_e32 v57, 2, v57
	ds_bpermute_b32 v57, v57, v10
	s_waitcnt lgkmcnt(0)
	v_add_f32_e32 v57, v10, v57
	v_cndmask_b32_e64 v10, v57, v10, s[18:19]
	v_subrev_u32_e32 v57, 32, v155
	v_cmp_lt_i32_e32 vcc, v57, v56
	v_readlane_b32 s18, v254, 39
	v_readlane_b32 s19, v254, 40
	v_cndmask_b32_e32 v56, v57, v155, vcc
	v_lshlrev_b32_e32 v56, 2, v56
	ds_bpermute_b32 v56, v56, v10
	s_waitcnt lgkmcnt(0)
	v_add_f32_e32 v56, v10, v56
	v_cndmask_b32_e64 v57, v56, v10, s[18:19]
	v_sub_f32_e32 v56, v57, v11
	ds_write_b64 v8, v[56:57]

.LBB0_568:
	s_or_b64 exec, exec, s[88:89]
	s_cmpk_gt_i32 s46, 0x3ff
	s_cselect_b64 s[68:69], -1, 0
	s_and_b64 vcc, exec, s[68:69]
	s_cbranch_vccnz .Lpfm_ms
	s_ashr_i32 s1, s46, 31
	s_lshr_b32 s1, s1, 26
	s_add_i32 s18, s46, s1
	s_and_b32 s1, s18, 0xffffffc0
	s_sub_i32 s26, s46, s1
	s_bfe_u32 s1, s18, 0x20006
	s_ashr_i32 s18, s18, 8
	s_ashr_i32 s19, s18, 31
	s_lshl_b32 s27, s26, 7
	s_lshl_b64 s[18:19], s[18:19], 13
	s_ashr_i32 s38, s27, 31
	s_add_u32 s88, s18, s27
	s_addc_u32 s89, s19, s38
	v_lshl_add_u64 v[0:1], s[88:89], 0, v[90:91]
	v_mov_b64_e32 v[10:11], s[28:29]
	v_lshl_add_u64 v[12:13], s[88:89], 0, v[94:95]
	v_lshl_add_u64 v[20:21], s[88:89], 0, v[98:99]
	v_mad_u64_u32 v[2:3], s[18:19], v0, s95, v[10:11]
	v_mad_u64_u32 v[14:15], s[18:19], v12, s95, v[10:11]
	v_mad_u64_u32 v[22:23], s[18:19], v20, s95, v[10:11]
	v_lshl_add_u64 v[28:29], s[88:89], 0, v[102:103]
	v_mad_i32_i24 v3, v1, s95, v3
	s_lshl_b32 s66, s1, 9
	v_mad_i32_i24 v15, v13, s95, v15
	v_mad_i32_i24 v23, v21, s95, v23
	v_mad_u64_u32 v[30:31], s[18:19], v28, s95, v[10:11]
	v_lshl_add_u64 v[0:1], v[2:3], 0, s[66:67]
	v_lshl_add_u64 v[2:3], s[88:89], 0, v[108:109]
	v_lshl_add_u64 v[12:13], v[14:15], 0, s[66:67]
	v_lshl_add_u64 v[14:15], s[88:89], 0, v[96:97]
	v_lshl_add_u64 v[20:21], v[22:23], 0, s[66:67]
	v_lshl_add_u64 v[22:23], s[88:89], 0, v[100:101]
	v_mad_i32_i24 v31, v29, s95, v31
	v_mad_u64_u32 v[4:5], s[18:19], v2, s95, v[10:11]
	v_mad_u64_u32 v[16:17], s[18:19], v14, s95, v[10:11]
	v_mad_u64_u32 v[24:25], s[18:19], v22, s95, v[10:11]
	v_lshl_add_u64 v[28:29], v[30:31], 0, s[66:67]
	v_lshl_add_u64 v[30:31], s[88:89], 0, v[104:105]
	v_mad_i32_i24 v5, v3, s95, v5
	v_mad_i32_i24 v17, v15, s95, v17
	v_mad_i32_i24 v25, v23, s95, v25
	v_mad_u64_u32 v[10:11], s[18:19], v30, s95, v[10:11]
	v_mov_b32_e32 v121, v9
	v_lshl_add_u64 v[2:3], v[4:5], 0, s[66:67]
	v_lshl_add_u64 v[14:15], v[16:17], 0, s[66:67]
	v_lshl_add_u64 v[22:23], v[24:25], 0, s[66:67]
	v_mad_i32_i24 v11, v31, s95, v11
	v_lshl_add_u64 v[0:1], v[0:1], 0, v[120:121]
	v_lshl_add_u64 v[4:5], v[2:3], 0, v[120:121]
	v_lshl_add_u64 v[12:13], v[12:13], 0, v[120:121]
	v_lshl_add_u64 v[16:17], v[14:15], 0, v[120:121]
	v_lshl_add_u64 v[20:21], v[20:21], 0, v[120:121]
	v_lshl_add_u64 v[24:25], v[22:23], 0, v[120:121]
	v_lshl_add_u64 v[28:29], v[28:29], 0, v[120:121]
	v_lshl_add_u64 v[10:11], v[10:11], 0, s[66:67]
	global_load_dwordx4 v[0:3], v[0:1], off offset:2048
	s_nop 0
	global_load_dwordx4 v[4:7], v[4:5], off offset:2048
	s_nop 0
	global_load_dwordx4 v[12:15], v[12:13], off offset:2048
	s_nop 0
	global_load_dwordx4 v[16:19], v[16:17], off offset:2048
	s_nop 0
	global_load_dwordx4 v[20:23], v[20:21], off offset:2048
	s_nop 0
	global_load_dwordx4 v[24:27], v[24:25], off offset:2048
	v_lshl_add_u64 v[10:11], v[10:11], 0, v[120:121]
	global_load_dwordx4 v[28:31], v[28:29], off offset:2048
	s_nop 0
	global_load_dwordx4 v[32:35], v[10:11], off offset:2048
	s_cmp_eq_u32 s26, 0
	v_readlane_b32 s26, v254, 11
	s_cselect_b64 s[90:91], -1, 0
	v_readlane_b32 s27, v254, 12
	v_mov_b32_e32 v38, v9
	v_mov_b32_e32 v39, v9
	s_and_b64 s[26:27], s[26:27], s[90:91]
	v_mov_b32_e32 v36, v9
	v_mov_b32_e32 v37, v9
	v_mov_b64_e32 v[42:43], v[38:39]
	s_lshl_b32 s18, s1, 7
	s_nor_b64 s[26:27], s[44:45], s[26:27]
	v_lshlrev_b32_e32 v56, 1, v106
	v_mov_b64_e32 v[40:41], v[36:37]
	s_and_saveexec_b64 s[92:93], s[26:27]
	s_cbranch_execz .LBB0_549
	v_lshl_add_u64 v[10:11], s[88:89], 0, v[92:93]
	v_mov_b64_e32 v[40:41], s[28:29]
	v_mad_u64_u32 v[40:41], s[26:27], v10, s95, v[40:41]
	v_mad_i32_i24 v41, v11, s95, v41
	s_lshl_b32 s66, s18, 1
	v_lshl_add_u64 v[10:11], v[40:41], 0, s[66:67]
	v_mov_b32_e32 v57, v9
	v_lshl_add_u64 v[10:11], v[10:11], 0, v[56:57]
	v_add_co_u32_e32 v10, vcc, 0xffffc000, v10
	s_nop 1
	v_addc_co_u32_e32 v11, vcc, -1, v11, vcc
	global_load_dwordx4 v[40:43], v[10:11], off offset:-1024

; DEVI void lds_barrier() { asm volatile("s_waitcnt lgkmcnt(0)\n\ts_barrier" ::: "memory"); }
; DEVI f32x4 mfma16(bf16x8 a, bf16x8 b, f32x4 c) { return __builtin_amdgcn_mfma_f32_16x16x32_bf16(a, b, c, 0, 0, 0); }
; template <int KIND>
; DEVI void mix_state_phase(unsigned char* smem, const MixArgs a) {
;     ...
;         lds_barrier();
;         f32x4 acc[2][8];
; #pragma unroll
;         for (int m = 0; m < 2; ++m)
; #pragma unroll
;             for (int n = 0; n < 8; ++n) acc[m][n] = (f32x4){0.f, 0.f, 0.f, 0.f};
; #pragma unroll
;         for (int ks = 0; ks < 4; ++ks) { bf16x8 af[2];
; #pragma unroll
;             for (int m = 0; m < 2; ++m) af[m] = tr_frag(VTF, VSP, ks * 32, wid * 32 + m * 16, lane);
; #pragma unroll
;             for (int n = 0; n < 8; ++n) { const bf16x8 bf = tr_frag_p(KT, LP, ks * 32, n, lane);
; #pragma unroll
;                 for (int m = 0; m < 2; ++m) acc[m][n] = mfma16(bf, af[m], acc[m][n]); } }
.Lpfm_ms:
	s_waitcnt lgkmcnt(0)
	s_barrier
	ds_read_b64_tr_b16 v[58:59], v143 offset:18496
	ds_read_b64_tr_b16 v[56:57], v143 offset:16384
	ds_read_b64_tr_b16 v[60:61], v143 offset:16416
	ds_read_b64_tr_b16 v[62:63], v143 offset:18528
	ds_read_b64_tr_b16 v[66:67], v144 offset:1088
	ds_read_b64_tr_b16 v[64:65], v144
	ds_read_b64_tr_b16 v[68:69], v144 offset:8
	ds_read_b64_tr_b16 v[70:71], v144 offset:1096
	ds_read_b64_tr_b16 v[80:81], v144 offset:64
	ds_read_b64_tr_b16 v[82:83], v144 offset:1152
	ds_read_b64_tr_b16 v[146:147], v144 offset:72
	ds_read_b64_tr_b16 v[148:149], v144 offset:1160
	ds_read_b64_tr_b16 v[176:177], v144 offset:128
	ds_read_b64_tr_b16 v[178:179], v144 offset:1216
	ds_read_b64_tr_b16 v[184:185], v144 offset:136
	ds_read_b64_tr_b16 v[186:187], v144 offset:1224
	ds_read_b64_tr_b16 v[192:193], v144 offset:192
	ds_read_b64_tr_b16 v[194:195], v144 offset:1280
	ds_read_b64_tr_b16 v[200:201], v144 offset:200
	ds_read_b64_tr_b16 v[202:203], v144 offset:1288
	s_waitcnt lgkmcnt(14)
	v_mfma_f32_16x16x32_bf16 v[72:75], v[64:67], v[56:59], 0
	s_lshl_b64 s[0:1], s[86:87], 16
	v_lshl_add_u64 v[10:11], v[118:119], 0, s[0:1]
	v_mfma_f32_16x16x32_bf16 v[64:67], v[64:67], v[60:63], 0
	s_waitcnt lgkmcnt(12)
	v_mfma_f32_16x16x32_bf16 v[76:79], v[68:71], v[56:59], 0
	v_mfma_f32_16x16x32_bf16 v[68:71], v[68:71], v[60:63], 0
	s_waitcnt lgkmcnt(10)
	v_mfma_f32_16x16x32_bf16 v[84:87], v[80:83], v[56:59], 0
	v_mfma_f32_16x16x32_bf16 v[80:83], v[80:83], v[60:63], 0
	s_waitcnt lgkmcnt(8)
	v_mfma_f32_16x16x32_bf16 v[150:153], v[146:149], v[56:59], 0
	v_mfma_f32_16x16x32_bf16 v[146:149], v[146:149], v[60:63], 0
	s_waitcnt lgkmcnt(6)
	v_mfma_f32_16x16x32_bf16 v[180:183], v[176:179], v[56:59], 0
	v_mfma_f32_16x16x32_bf16 v[176:179], v[176:179], v[60:63], 0
	s_waitcnt lgkmcnt(4)
	v_mfma_f32_16x16x32_bf16 v[188:191], v[184:187], v[56:59], 0
	v_mfma_f32_16x16x32_bf16 v[184:187], v[184:187], v[60:63], 0
	s_waitcnt lgkmcnt(2)
	v_mfma_f32_16x16x32_bf16 v[196:199], v[192:195], v[56:59], 0
	v_mfma_f32_16x16x32_bf16 v[192:195], v[192:195], v[60:63], 0
	s_waitcnt lgkmcnt(0)
	v_mfma_f32_16x16x32_bf16 v[56:59], v[200:203], v[56:59], 0
	v_mfma_f32_16x16x32_bf16 v[60:63], v[200:203], v[60:63], 0
	ds_read_b64_tr_b16 v[200:201], v143 offset:33280
	ds_read_b64_tr_b16 v[202:203], v143 offset:35392
	ds_read_b64_tr_b16 v[204:205], v143 offset:33312
	ds_read_b64_tr_b16 v[206:207], v143 offset:35424
	ds_read_b64_tr_b16 v[214:215], v144 offset:8704
	ds_read_b64_tr_b16 v[216:217], v144 offset:9792
	s_waitcnt lgkmcnt(0)
	v_mfma_f32_16x16x32_bf16 v[72:75], v[214:217], v[200:203], v[72:75]
	v_mfma_f32_16x16x32_bf16 v[64:67], v[214:217], v[204:207], v[64:67]
	ds_read_b64_tr_b16 v[214:215], v144 offset:8712
	ds_read_b64_tr_b16 v[216:217], v144 offset:9800
	s_waitcnt lgkmcnt(0)
	v_mfma_f32_16x16x32_bf16 v[76:79], v[214:217], v[200:203], v[76:79]
	v_mfma_f32_16x16x32_bf16 v[68:71], v[214:217], v[204:207], v[68:71]
	ds_read_b64_tr_b16 v[214:215], v144 offset:8768
	ds_read_b64_tr_b16 v[216:217], v144 offset:9856
	s_waitcnt lgkmcnt(0)
	v_mfma_f32_16x16x32_bf16 v[84:87], v[214:217], v[200:203], v[84:87]
	v_mfma_f32_16x16x32_bf16 v[80:83], v[214:217], v[204:207], v[80:83]
	ds_read_b64_tr_b16 v[214:215], v144 offset:8776
	ds_read_b64_tr_b16 v[216:217], v144 offset:9864
	s_waitcnt lgkmcnt(0)
	v_mfma_f32_16x16x32_bf16 v[150:153], v[214:217], v[200:203], v[150:153]
	v_mfma_f32_16x16x32_bf16 v[146:149], v[214:217], v[204:207], v[146:149]
	ds_read_b64_tr_b16 v[214:215], v144 offset:8832
	ds_read_b64_tr_b16 v[216:217], v144 offset:9920
	s_waitcnt lgkmcnt(0)
	v_mfma_f32_16x16x32_bf16 v[180:183], v[214:217], v[200:203], v[180:183]
	v_mfma_f32_16x16x32_bf16 v[176:179], v[214:217], v[204:207], v[176:179]
	ds_read_b64_tr_b16 v[214:215], v144 offset:8840
	ds_read_b64_tr_b16 v[216:217], v144 offset:9928
	s_waitcnt lgkmcnt(0)
	v_mfma_f32_16x16x32_bf16 v[188:191], v[214:217], v[200:203], v[188:191]
	v_mfma_f32_16x16x32_bf16 v[184:187], v[214:217], v[204:207], v[184:187]
	ds_read_b64_tr_b16 v[214:215], v144 offset:8896
	ds_read_b64_tr_b16 v[216:217], v144 offset:9984
	s_waitcnt lgkmcnt(0)
	v_mfma_f32_16x16x32_bf16 v[196:199], v[214:217], v[200:203], v[196:199]
	v_mfma_f32_16x16x32_bf16 v[192:195], v[214:217], v[204:207], v[192:195]
	ds_read_b64_tr_b16 v[214:215], v144 offset:8904
	ds_read_b64_tr_b16 v[216:217], v144 offset:9992
	s_waitcnt lgkmcnt(0)
	v_mfma_f32_16x16x32_bf16 v[56:59], v[214:217], v[200:203], v[56:59]
	v_mfma_f32_16x16x32_bf16 v[60:63], v[214:217], v[204:207], v[60:63]
	ds_read_b64_tr_b16 v[200:201], v143 offset:50176
	ds_read_b64_tr_b16 v[202:203], v143 offset:52288
	ds_read_b64_tr_b16 v[204:205], v143 offset:50208
	ds_read_b64_tr_b16 v[206:207], v143 offset:52320
	ds_read_b64_tr_b16 v[214:215], v144 offset:17408
	ds_read_b64_tr_b16 v[216:217], v144 offset:18496
	s_waitcnt lgkmcnt(0)
	v_mfma_f32_16x16x32_bf16 v[72:75], v[214:217], v[200:203], v[72:75]
	v_mfma_f32_16x16x32_bf16 v[64:67], v[214:217], v[204:207], v[64:67]
	ds_read_b64_tr_b16 v[214:215], v144 offset:17416
	ds_read_b64_tr_b16 v[216:217], v144 offset:18504
	s_waitcnt lgkmcnt(0)
	v_mfma_f32_16x16x32_bf16 v[76:79], v[214:217], v[200:203], v[76:79]
	v_mfma_f32_16x16x32_bf16 v[68:71], v[214:217], v[204:207], v[68:71]
	ds_read_b64_tr_b16 v[214:215], v144 offset:17472
	ds_read_b64_tr_b16 v[216:217], v144 offset:18560
	s_waitcnt lgkmcnt(0)
; DEVI float bf2f(u16 b) { return __uint_as_float(((unsigned)b) << 16); }
; DEVI f32x4 mfma16(bf16x8 a, bf16x8 b, f32x4 c) { return __builtin_amdgcn_mfma_f32_16x16x32_bf16(a, b, c, 0, 0, 0); }
; DEVI u32x4 pk8(f32x4 a, f32x4 b) { u32x4 w; w.x = cvt_pk(a[0], a[1]); w.y = cvt_pk(a[2], a[3]); w.z = cvt_pk(b[0], b[1]); w.w = cvt_pk(b[2], b[3]); return w; }
; template <int KIND>
; DEVI void mix_state_phase(unsigned char* smem, const MixArgs a) {
;     ...
; #pragma unroll
;         for (int ks = 0; ks < 4; ++ks) { bf16x8 af[2];
; #pragma unroll
;             for (int m = 0; m < 2; ++m) af[m] = tr_frag(VTF, VSP, ks * 32, wid * 32 + m * 16, lane);
; #pragma unroll
;             for (int n = 0; n < 8; ++n) { const bf16x8 bf = tr_frag_p(KT, LP, ks * 32, n, lane);
; #pragma unroll
;                 for (int m = 0; m < 2; ++m) acc[m][n] = mfma16(bf, af[m], acc[m][n]); } }
;         u16* st = a.states + (size_t)item * 256 * 128;
; #pragma unroll
;         for (int m = 0; m < 2; ++m)
; #pragma unroll
;             for (int n = 0; n < 8; n += 2) *(u32x4*)(st + (wid * 32 + m * 16 + fr) * 128 + n * 16 + fq * 8) = pk8(acc[m][n], acc[m][n + 1]);
;         if (KIND == 0 && tid < 128) { float sum = 0.f; for (int t = 0; t < 128; ++t) sum += bf2f(KT[t * LP + tid]); a.dn[(size_t)item * 128 + tid] = sum; a.dec[(size_t)item * 128 + tid] = __expf(fB[127]); }
	v_mfma_f32_16x16x32_bf16 v[84:87], v[214:217], v[200:203], v[84:87]
	v_mfma_f32_16x16x32_bf16 v[80:83], v[214:217], v[204:207], v[80:83]
	ds_read_b64_tr_b16 v[214:215], v144 offset:17480
	ds_read_b64_tr_b16 v[216:217], v144 offset:18568
	s_waitcnt lgkmcnt(0)
	v_mfma_f32_16x16x32_bf16 v[150:153], v[214:217], v[200:203], v[150:153]
	v_mfma_f32_16x16x32_bf16 v[146:149], v[214:217], v[204:207], v[146:149]
	ds_read_b64_tr_b16 v[214:215], v144 offset:17536
	ds_read_b64_tr_b16 v[216:217], v144 offset:18624
	s_waitcnt lgkmcnt(0)
	v_mfma_f32_16x16x32_bf16 v[180:183], v[214:217], v[200:203], v[180:183]
	v_mfma_f32_16x16x32_bf16 v[176:179], v[214:217], v[204:207], v[176:179]
	ds_read_b64_tr_b16 v[214:215], v144 offset:17544
	ds_read_b64_tr_b16 v[216:217], v144 offset:18632
	s_waitcnt lgkmcnt(0)
	v_mfma_f32_16x16x32_bf16 v[188:191], v[214:217], v[200:203], v[188:191]
	v_mfma_f32_16x16x32_bf16 v[184:187], v[214:217], v[204:207], v[184:187]
	ds_read_b64_tr_b16 v[214:215], v144 offset:17600
	ds_read_b64_tr_b16 v[216:217], v144 offset:18688
	s_waitcnt lgkmcnt(0)
	v_mfma_f32_16x16x32_bf16 v[196:199], v[214:217], v[200:203], v[196:199]
	v_mfma_f32_16x16x32_bf16 v[192:195], v[214:217], v[204:207], v[192:195]
	ds_read_b64_tr_b16 v[214:215], v144 offset:17608
	ds_read_b64_tr_b16 v[216:217], v144 offset:18696
	s_waitcnt lgkmcnt(0)
	v_mfma_f32_16x16x32_bf16 v[200:203], v[214:217], v[200:203], v[56:59]
	v_mfma_f32_16x16x32_bf16 v[60:63], v[214:217], v[204:207], v[60:63]
	ds_read_b64_tr_b16 v[206:207], v145 offset:52288
	ds_read_b64_tr_b16 v[204:205], v145 offset:50176
	ds_read_b64_tr_b16 v[214:215], v145 offset:50208
	ds_read_b64_tr_b16 v[216:217], v145 offset:52320
	ds_read_b64_tr_b16 v[56:57], v144 offset:26112
	ds_read_b64_tr_b16 v[58:59], v144 offset:27200
	s_waitcnt lgkmcnt(0)
	v_mfma_f32_16x16x32_bf16 v[72:75], v[56:59], v[204:207], v[72:75]
	v_mfma_f32_16x16x32_bf16 v[56:59], v[56:59], v[214:217], v[64:67]
	s_nop 2
	ds_read_b64_tr_b16 v[64:65], v144 offset:26120
	ds_read_b64_tr_b16 v[66:67], v144 offset:27208
	s_nop 1
	v_cvt_pk_bf16_f32 v72, v72, v73
	v_cvt_pk_bf16_f32 v73, v74, v75
	s_waitcnt lgkmcnt(0)
	v_mfma_f32_16x16x32_bf16 v[76:79], v[64:67], v[204:207], v[76:79]
	v_cvt_pk_bf16_f32 v56, v56, v57
	v_cvt_pk_bf16_f32 v57, v58, v59
	v_mfma_f32_16x16x32_bf16 v[64:67], v[64:67], v[214:217], v[68:71]
	s_nop 2
	ds_read_b64_tr_b16 v[68:69], v144 offset:26176
	ds_read_b64_tr_b16 v[70:71], v144 offset:27264
	v_cvt_pk_bf16_f32 v74, v76, v77
	v_cvt_pk_bf16_f32 v75, v78, v79
	s_waitcnt lgkmcnt(0)
	v_mfma_f32_16x16x32_bf16 v[84:87], v[68:71], v[204:207], v[84:87]
	v_cvt_pk_bf16_f32 v58, v64, v65
	v_cvt_pk_bf16_f32 v59, v66, v67
	v_mfma_f32_16x16x32_bf16 v[68:71], v[68:71], v[214:217], v[80:83]
	s_nop 2
	ds_read_b64_tr_b16 v[80:81], v144 offset:26184
	ds_read_b64_tr_b16 v[82:83], v144 offset:27272
	s_waitcnt lgkmcnt(0)
	v_mfma_f32_16x16x32_bf16 v[150:153], v[80:83], v[204:207], v[150:153]
	v_mfma_f32_16x16x32_bf16 v[80:83], v[80:83], v[214:217], v[146:149]
	s_nop 2
	ds_read_b64_tr_b16 v[146:147], v144 offset:26240
	ds_read_b64_tr_b16 v[148:149], v144 offset:27328
	s_waitcnt lgkmcnt(0)
	v_mfma_f32_16x16x32_bf16 v[180:183], v[146:149], v[204:207], v[180:183]
	v_mfma_f32_16x16x32_bf16 v[146:149], v[146:149], v[214:217], v[176:179]
	s_nop 2
	ds_read_b64_tr_b16 v[176:177], v144 offset:26248
	ds_read_b64_tr_b16 v[178:179], v144 offset:27336
	s_waitcnt lgkmcnt(0)
	v_mfma_f32_16x16x32_bf16 v[188:191], v[176:179], v[204:207], v[188:191]
	v_mfma_f32_16x16x32_bf16 v[176:179], v[176:179], v[214:217], v[184:187]
	s_nop 2
	ds_read_b64_tr_b16 v[184:185], v144 offset:26304
	ds_read_b64_tr_b16 v[186:187], v144 offset:27392
	s_waitcnt lgkmcnt(0)
	v_mfma_f32_16x16x32_bf16 v[196:199], v[184:187], v[204:207], v[196:199]
	v_mfma_f32_16x16x32_bf16 v[184:187], v[184:187], v[214:217], v[192:195]
	s_nop 2
	ds_read_b64_tr_b16 v[192:193], v144 offset:26312
	ds_read_b64_tr_b16 v[194:195], v144 offset:27400
	global_store_dwordx4 v[10:11], v[72:75], off
	s_waitcnt lgkmcnt(0)
	v_mfma_f32_16x16x32_bf16 v[200:203], v[192:195], v[204:207], v[200:203]
	v_cvt_pk_bf16_f32 v72, v84, v85
	v_cvt_pk_bf16_f32 v73, v86, v87
	v_cvt_pk_bf16_f32 v74, v150, v151
	v_cvt_pk_bf16_f32 v75, v152, v153
	global_store_dwordx4 v[10:11], v[72:75], off offset:64
	v_mfma_f32_16x16x32_bf16 v[60:63], v[192:195], v[214:217], v[60:63]
	s_nop 0
	v_cvt_pk_bf16_f32 v72, v180, v181
	v_cvt_pk_bf16_f32 v73, v182, v183
	v_cvt_pk_bf16_f32 v74, v188, v189
	v_cvt_pk_bf16_f32 v75, v190, v191
	global_store_dwordx4 v[10:11], v[72:75], off offset:128
	s_nop 1
	v_cvt_pk_bf16_f32 v72, v196, v197
	v_cvt_pk_bf16_f32 v73, v198, v199
	v_cvt_pk_bf16_f32 v74, v200, v201
	v_cvt_pk_bf16_f32 v75, v202, v203
	global_store_dwordx4 v[10:11], v[72:75], off offset:192
	v_add_co_u32_e32 v10, vcc, s50, v10
	s_nop 1
	v_addc_co_u32_e32 v11, vcc, 0, v11, vcc
	global_store_dwordx4 v[10:11], v[56:59], off
	s_nop 1
	v_cvt_pk_bf16_f32 v56, v68, v69
	v_cvt_pk_bf16_f32 v57, v70, v71
	v_cvt_pk_bf16_f32 v58, v80, v81
	v_cvt_pk_bf16_f32 v59, v82, v83
	global_store_dwordx4 v[10:11], v[56:59], off offset:64
	s_nop 1
	v_cvt_pk_bf16_f32 v56, v146, v147
	v_cvt_pk_bf16_f32 v57, v148, v149
	v_cvt_pk_bf16_f32 v58, v176, v177
	v_cvt_pk_bf16_f32 v59, v178, v179
	global_store_dwordx4 v[10:11], v[56:59], off offset:128
	s_nop 1
	v_cvt_pk_bf16_f32 v56, v184, v185
	v_cvt_pk_bf16_f32 v57, v186, v187
	v_cvt_pk_bf16_f32 v58, v60, v61
	v_cvt_pk_bf16_f32 v59, v62, v63
	global_store_dwordx4 v[10:11], v[56:59], off offset:192
	s_and_saveexec_b64 s[88:89], s[2:3]
	s_cbranch_execz .LBB0_537
	v_mov_b32_e32 v8, 0
	s_mov_b32 s0, 0
